# GLA chunk-state scan inner loop hand-written: 16 chunks of loads in flight with counted waits (on top of fp6 + gate software-pipelined loops and layer-1 rebalance)
# speedup vs baseline: 1.0118x; 1.0118x over previous
.LBB0_518:
	s_add_u32 s22, s92, 0x17000000
	s_addc_u32 s23, s93, 0
	s_add_u32 s24, s92, 0xc00000
	s_addc_u32 s25, s93, 0
	s_mov_b32 s26, s4
	s_mov_b32 s27, s5
	v_lshlrev_b32_e32 v42, 1, v4
	global_load_dwordx2 v[106:107], v6, s[22:23]
	global_load_dwordx2 v[138:139], v2, s[24:25]
	s_add_u32 s22, s22, 0x20000
	s_addc_u32 s23, s23, 0
	s_add_u32 s24, s24, 0x200
	s_addc_u32 s25, s25, 0
	global_load_dwordx2 v[108:109], v6, s[22:23]
	global_load_dwordx2 v[140:141], v2, s[24:25]
	s_add_u32 s22, s22, 0x20000
	s_addc_u32 s23, s23, 0
	s_add_u32 s24, s24, 0x200
	s_addc_u32 s25, s25, 0
	global_load_dwordx2 v[110:111], v6, s[22:23]
	global_load_dwordx2 v[142:143], v2, s[24:25]
	s_add_u32 s22, s22, 0x20000
	s_addc_u32 s23, s23, 0
	s_add_u32 s24, s24, 0x200
	s_addc_u32 s25, s25, 0
	global_load_dwordx2 v[112:113], v6, s[22:23]
	global_load_dwordx2 v[144:145], v2, s[24:25]
	s_add_u32 s22, s22, 0x20000
	s_addc_u32 s23, s23, 0
	s_add_u32 s24, s24, 0x200
	s_addc_u32 s25, s25, 0
	global_load_dwordx2 v[114:115], v6, s[22:23]
	global_load_dwordx2 v[146:147], v2, s[24:25]
	s_add_u32 s22, s22, 0x20000
	s_addc_u32 s23, s23, 0
	s_add_u32 s24, s24, 0x200
	s_addc_u32 s25, s25, 0
	global_load_dwordx2 v[116:117], v6, s[22:23]
	global_load_dwordx2 v[148:149], v2, s[24:25]
	s_add_u32 s22, s22, 0x20000
	s_addc_u32 s23, s23, 0
	s_add_u32 s24, s24, 0x200
	s_addc_u32 s25, s25, 0
	global_load_dwordx2 v[118:119], v6, s[22:23]
	global_load_dwordx2 v[150:151], v2, s[24:25]
	s_add_u32 s22, s22, 0x20000
	s_addc_u32 s23, s23, 0
	s_add_u32 s24, s24, 0x200
	s_addc_u32 s25, s25, 0
	global_load_dwordx2 v[120:121], v6, s[22:23]
	global_load_dwordx2 v[152:153], v2, s[24:25]
	s_add_u32 s22, s22, 0x20000
	s_addc_u32 s23, s23, 0
	s_add_u32 s24, s24, 0x200
	s_addc_u32 s25, s25, 0
	global_load_dwordx2 v[122:123], v6, s[22:23]
	global_load_dwordx2 v[154:155], v2, s[24:25]
	s_add_u32 s22, s22, 0x20000
	s_addc_u32 s23, s23, 0
	s_add_u32 s24, s24, 0x200
	s_addc_u32 s25, s25, 0
	global_load_dwordx2 v[124:125], v6, s[22:23]
	global_load_dwordx2 v[156:157], v2, s[24:25]
	s_add_u32 s22, s22, 0x20000
	s_addc_u32 s23, s23, 0
	s_add_u32 s24, s24, 0x200
	s_addc_u32 s25, s25, 0
	global_load_dwordx2 v[126:127], v6, s[22:23]
	global_load_dwordx2 v[158:159], v2, s[24:25]
	s_add_u32 s22, s22, 0x20000
	s_addc_u32 s23, s23, 0
	s_add_u32 s24, s24, 0x200
	s_addc_u32 s25, s25, 0
	global_load_dwordx2 v[128:129], v6, s[22:23]
	global_load_dwordx2 v[160:161], v2, s[24:25]
	s_add_u32 s22, s22, 0x20000
	s_addc_u32 s23, s23, 0
	s_add_u32 s24, s24, 0x200
	s_addc_u32 s25, s25, 0
	global_load_dwordx2 v[130:131], v6, s[22:23]
	global_load_dwordx2 v[162:163], v2, s[24:25]
	s_add_u32 s22, s22, 0x20000
	s_addc_u32 s23, s23, 0
	s_add_u32 s24, s24, 0x200
	s_addc_u32 s25, s25, 0
	global_load_dwordx2 v[132:133], v6, s[22:23]
	global_load_dwordx2 v[164:165], v2, s[24:25]
	s_add_u32 s22, s22, 0x20000
	s_addc_u32 s23, s23, 0
	s_add_u32 s24, s24, 0x200
	s_addc_u32 s25, s25, 0
	global_load_dwordx2 v[134:135], v6, s[22:23]
	global_load_dwordx2 v[166:167], v2, s[24:25]
	s_add_u32 s22, s22, 0x20000
	s_addc_u32 s23, s23, 0
	s_add_u32 s24, s24, 0x200
	s_addc_u32 s25, s25, 0
	global_load_dwordx2 v[136:137], v6, s[22:23]
	global_load_dwordx2 v[168:169], v2, s[24:25]
	s_add_u32 s22, s22, 0x20000
	s_addc_u32 s23, s23, 0
	s_add_u32 s24, s24, 0x200
	s_addc_u32 s25, s25, 0
	s_waitcnt vmcnt(30)
	v_cvt_pk_bf16_f32 v43, v8, v9
	global_store_dword v42, v43, s[26:27]
	v_pk_fma_f32 v[8:9], v[8:9], v[138:139], v[106:107]
	s_add_u32 s26, s26, 0x10000
	s_addc_u32 s27, s27, 0
	global_load_dwordx2 v[106:107], v6, s[22:23]
	global_load_dwordx2 v[138:139], v2, s[24:25]
	s_add_u32 s22, s22, 0x20000
	s_addc_u32 s23, s23, 0
	s_add_u32 s24, s24, 0x200
	s_addc_u32 s25, s25, 0
	s_waitcnt vmcnt(31)
	v_cvt_pk_bf16_f32 v44, v8, v9
	global_store_dword v42, v44, s[26:27]
	v_pk_fma_f32 v[8:9], v[8:9], v[140:141], v[108:109]
	s_add_u32 s26, s26, 0x10000
	s_addc_u32 s27, s27, 0
	global_load_dwordx2 v[108:109], v6, s[22:23]
	global_load_dwordx2 v[140:141], v2, s[24:25]
	s_add_u32 s22, s22, 0x20000
	s_addc_u32 s23, s23, 0
	s_add_u32 s24, s24, 0x200
	s_addc_u32 s25, s25, 0
	s_waitcnt vmcnt(32)
	v_cvt_pk_bf16_f32 v43, v8, v9
	global_store_dword v42, v43, s[26:27]
	v_pk_fma_f32 v[8:9], v[8:9], v[142:143], v[110:111]
	s_add_u32 s26, s26, 0x10000
	s_addc_u32 s27, s27, 0
	global_load_dwordx2 v[110:111], v6, s[22:23]
	global_load_dwordx2 v[142:143], v2, s[24:25]
	s_add_u32 s22, s22, 0x20000
	s_addc_u32 s23, s23, 0
	s_add_u32 s24, s24, 0x200
	s_addc_u32 s25, s25, 0
	s_waitcnt vmcnt(33)
	v_cvt_pk_bf16_f32 v44, v8, v9
	global_store_dword v42, v44, s[26:27]
	v_pk_fma_f32 v[8:9], v[8:9], v[144:145], v[112:113]
	s_add_u32 s26, s26, 0x10000
	s_addc_u32 s27, s27, 0
	global_load_dwordx2 v[112:113], v6, s[22:23]
	global_load_dwordx2 v[144:145], v2, s[24:25]
	s_add_u32 s22, s22, 0x20000
	s_addc_u32 s23, s23, 0
	s_add_u32 s24, s24, 0x200
	s_addc_u32 s25, s25, 0
	s_waitcnt vmcnt(34)
	v_cvt_pk_bf16_f32 v43, v8, v9
	global_store_dword v42, v43, s[26:27]
	v_pk_fma_f32 v[8:9], v[8:9], v[146:147], v[114:115]
	s_add_u32 s26, s26, 0x10000
	s_addc_u32 s27, s27, 0
	global_load_dwordx2 v[114:115], v6, s[22:23]
	global_load_dwordx2 v[146:147], v2, s[24:25]
	s_add_u32 s22, s22, 0x20000
	s_addc_u32 s23, s23, 0
	s_add_u32 s24, s24, 0x200
	s_addc_u32 s25, s25, 0
	s_waitcnt vmcnt(35)
	v_cvt_pk_bf16_f32 v44, v8, v9
	global_store_dword v42, v44, s[26:27]
	v_pk_fma_f32 v[8:9], v[8:9], v[148:149], v[116:117]
	s_add_u32 s26, s26, 0x10000
	s_addc_u32 s27, s27, 0
	global_load_dwordx2 v[116:117], v6, s[22:23]
	global_load_dwordx2 v[148:149], v2, s[24:25]
	s_add_u32 s22, s22, 0x20000
	s_addc_u32 s23, s23, 0
	s_add_u32 s24, s24, 0x200
	s_addc_u32 s25, s25, 0
	s_waitcnt vmcnt(36)
	v_cvt_pk_bf16_f32 v43, v8, v9
	global_store_dword v42, v43, s[26:27]
	v_pk_fma_f32 v[8:9], v[8:9], v[150:151], v[118:119]
	s_add_u32 s26, s26, 0x10000
	s_addc_u32 s27, s27, 0
	global_load_dwordx2 v[118:119], v6, s[22:23]
	global_load_dwordx2 v[150:151], v2, s[24:25]
	s_add_u32 s22, s22, 0x20000
	s_addc_u32 s23, s23, 0
	s_add_u32 s24, s24, 0x200
	s_addc_u32 s25, s25, 0
	s_waitcnt vmcnt(37)
	v_cvt_pk_bf16_f32 v44, v8, v9
	global_store_dword v42, v44, s[26:27]
	v_pk_fma_f32 v[8:9], v[8:9], v[152:153], v[120:121]
	s_add_u32 s26, s26, 0x10000
	s_addc_u32 s27, s27, 0
	global_load_dwordx2 v[120:121], v6, s[22:23]
	global_load_dwordx2 v[152:153], v2, s[24:25]
	s_add_u32 s22, s22, 0x20000
	s_addc_u32 s23, s23, 0
	s_add_u32 s24, s24, 0x200
	s_addc_u32 s25, s25, 0
	s_waitcnt vmcnt(38)
	v_cvt_pk_bf16_f32 v43, v8, v9
	global_store_dword v42, v43, s[26:27]
	v_pk_fma_f32 v[8:9], v[8:9], v[154:155], v[122:123]
	s_add_u32 s26, s26, 0x10000
	s_addc_u32 s27, s27, 0
	global_load_dwordx2 v[122:123], v6, s[22:23]
	global_load_dwordx2 v[154:155], v2, s[24:25]
	s_add_u32 s22, s22, 0x20000
	s_addc_u32 s23, s23, 0
	s_add_u32 s24, s24, 0x200
	s_addc_u32 s25, s25, 0
	s_waitcnt vmcnt(39)
	v_cvt_pk_bf16_f32 v44, v8, v9
	global_store_dword v42, v44, s[26:27]
	v_pk_fma_f32 v[8:9], v[8:9], v[156:157], v[124:125]
	s_add_u32 s26, s26, 0x10000
	s_addc_u32 s27, s27, 0
	global_load_dwordx2 v[124:125], v6, s[22:23]
	global_load_dwordx2 v[156:157], v2, s[24:25]
	s_add_u32 s22, s22, 0x20000
	s_addc_u32 s23, s23, 0
	s_add_u32 s24, s24, 0x200
	s_addc_u32 s25, s25, 0
	s_waitcnt vmcnt(40)
	v_cvt_pk_bf16_f32 v43, v8, v9
	global_store_dword v42, v43, s[26:27]
	v_pk_fma_f32 v[8:9], v[8:9], v[158:159], v[126:127]
	s_add_u32 s26, s26, 0x10000
	s_addc_u32 s27, s27, 0
	global_load_dwordx2 v[126:127], v6, s[22:23]
	global_load_dwordx2 v[158:159], v2, s[24:25]
	s_add_u32 s22, s22, 0x20000
	s_addc_u32 s23, s23, 0
	s_add_u32 s24, s24, 0x200
	s_addc_u32 s25, s25, 0
	s_waitcnt vmcnt(41)
	v_cvt_pk_bf16_f32 v44, v8, v9
	global_store_dword v42, v44, s[26:27]
	v_pk_fma_f32 v[8:9], v[8:9], v[160:161], v[128:129]
	s_add_u32 s26, s26, 0x10000
	s_addc_u32 s27, s27, 0
	global_load_dwordx2 v[128:129], v6, s[22:23]
	global_load_dwordx2 v[160:161], v2, s[24:25]
	s_add_u32 s22, s22, 0x20000
	s_addc_u32 s23, s23, 0
	s_add_u32 s24, s24, 0x200
	s_addc_u32 s25, s25, 0
	s_waitcnt vmcnt(42)
	v_cvt_pk_bf16_f32 v43, v8, v9
	global_store_dword v42, v43, s[26:27]
	v_pk_fma_f32 v[8:9], v[8:9], v[162:163], v[130:131]
	s_add_u32 s26, s26, 0x10000
	s_addc_u32 s27, s27, 0
	global_load_dwordx2 v[130:131], v6, s[22:23]
	global_load_dwordx2 v[162:163], v2, s[24:25]
	s_add_u32 s22, s22, 0x20000
	s_addc_u32 s23, s23, 0
	s_add_u32 s24, s24, 0x200
	s_addc_u32 s25, s25, 0
	s_waitcnt vmcnt(43)
	v_cvt_pk_bf16_f32 v44, v8, v9
	global_store_dword v42, v44, s[26:27]
	v_pk_fma_f32 v[8:9], v[8:9], v[164:165], v[132:133]
	s_add_u32 s26, s26, 0x10000
	s_addc_u32 s27, s27, 0
	global_load_dwordx2 v[132:133], v6, s[22:23]
	global_load_dwordx2 v[164:165], v2, s[24:25]
	s_add_u32 s22, s22, 0x20000
	s_addc_u32 s23, s23, 0
	s_add_u32 s24, s24, 0x200
	s_addc_u32 s25, s25, 0
	s_waitcnt vmcnt(44)
	v_cvt_pk_bf16_f32 v43, v8, v9
	global_store_dword v42, v43, s[26:27]
	v_pk_fma_f32 v[8:9], v[8:9], v[166:167], v[134:135]
	s_add_u32 s26, s26, 0x10000
	s_addc_u32 s27, s27, 0
	global_load_dwordx2 v[134:135], v6, s[22:23]
	global_load_dwordx2 v[166:167], v2, s[24:25]
	s_add_u32 s22, s22, 0x20000
	s_addc_u32 s23, s23, 0
	s_add_u32 s24, s24, 0x200
	s_addc_u32 s25, s25, 0
	s_waitcnt vmcnt(45)
	v_cvt_pk_bf16_f32 v44, v8, v9
	global_store_dword v42, v44, s[26:27]
	v_pk_fma_f32 v[8:9], v[8:9], v[168:169], v[136:137]
	s_add_u32 s26, s26, 0x10000
	s_addc_u32 s27, s27, 0
	global_load_dwordx2 v[136:137], v6, s[22:23]
	global_load_dwordx2 v[168:169], v2, s[24:25]
	s_add_u32 s22, s22, 0x20000
	s_addc_u32 s23, s23, 0
	s_add_u32 s24, s24, 0x200
	s_addc_u32 s25, s25, 0
	s_waitcnt vmcnt(45)
	v_cvt_pk_bf16_f32 v43, v8, v9
	global_store_dword v42, v43, s[26:27]
	v_pk_fma_f32 v[8:9], v[8:9], v[138:139], v[106:107]
	s_add_u32 s26, s26, 0x10000
	s_addc_u32 s27, s27, 0
	global_load_dwordx2 v[106:107], v6, s[22:23]
	global_load_dwordx2 v[138:139], v2, s[24:25]
	s_add_u32 s22, s22, 0x20000
	s_addc_u32 s23, s23, 0
	s_add_u32 s24, s24, 0x200
	s_addc_u32 s25, s25, 0
	s_waitcnt vmcnt(45)
	v_cvt_pk_bf16_f32 v44, v8, v9
	global_store_dword v42, v44, s[26:27]
	v_pk_fma_f32 v[8:9], v[8:9], v[140:141], v[108:109]
	s_add_u32 s26, s26, 0x10000
	s_addc_u32 s27, s27, 0
	global_load_dwordx2 v[108:109], v6, s[22:23]
	global_load_dwordx2 v[140:141], v2, s[24:25]
	s_add_u32 s22, s22, 0x20000
	s_addc_u32 s23, s23, 0
	s_add_u32 s24, s24, 0x200
	s_addc_u32 s25, s25, 0
	s_waitcnt vmcnt(45)
	v_cvt_pk_bf16_f32 v43, v8, v9
	global_store_dword v42, v43, s[26:27]
	v_pk_fma_f32 v[8:9], v[8:9], v[142:143], v[110:111]
	s_add_u32 s26, s26, 0x10000
	s_addc_u32 s27, s27, 0
	global_load_dwordx2 v[110:111], v6, s[22:23]
	global_load_dwordx2 v[142:143], v2, s[24:25]
	s_add_u32 s22, s22, 0x20000
	s_addc_u32 s23, s23, 0
	s_add_u32 s24, s24, 0x200
	s_addc_u32 s25, s25, 0
	s_waitcnt vmcnt(45)
	v_cvt_pk_bf16_f32 v44, v8, v9
	global_store_dword v42, v44, s[26:27]
	v_pk_fma_f32 v[8:9], v[8:9], v[144:145], v[112:113]
	s_add_u32 s26, s26, 0x10000
	s_addc_u32 s27, s27, 0
	global_load_dwordx2 v[112:113], v6, s[22:23]
	global_load_dwordx2 v[144:145], v2, s[24:25]
	s_add_u32 s22, s22, 0x20000
	s_addc_u32 s23, s23, 0
	s_add_u32 s24, s24, 0x200
	s_addc_u32 s25, s25, 0
	s_waitcnt vmcnt(45)
	v_cvt_pk_bf16_f32 v43, v8, v9
	global_store_dword v42, v43, s[26:27]
	v_pk_fma_f32 v[8:9], v[8:9], v[146:147], v[114:115]
	s_add_u32 s26, s26, 0x10000
	s_addc_u32 s27, s27, 0
	global_load_dwordx2 v[114:115], v6, s[22:23]
	global_load_dwordx2 v[146:147], v2, s[24:25]
	s_add_u32 s22, s22, 0x20000
	s_addc_u32 s23, s23, 0
	s_add_u32 s24, s24, 0x200
	s_addc_u32 s25, s25, 0
	s_waitcnt vmcnt(45)
	v_cvt_pk_bf16_f32 v44, v8, v9
	global_store_dword v42, v44, s[26:27]
	v_pk_fma_f32 v[8:9], v[8:9], v[148:149], v[116:117]
	s_add_u32 s26, s26, 0x10000
	s_addc_u32 s27, s27, 0
	global_load_dwordx2 v[116:117], v6, s[22:23]
	global_load_dwordx2 v[148:149], v2, s[24:25]
	s_add_u32 s22, s22, 0x20000
	s_addc_u32 s23, s23, 0
	s_add_u32 s24, s24, 0x200
	s_addc_u32 s25, s25, 0
	s_waitcnt vmcnt(45)
	v_cvt_pk_bf16_f32 v43, v8, v9
	global_store_dword v42, v43, s[26:27]
	v_pk_fma_f32 v[8:9], v[8:9], v[150:151], v[118:119]
	s_add_u32 s26, s26, 0x10000
	s_addc_u32 s27, s27, 0
	global_load_dwordx2 v[118:119], v6, s[22:23]
	global_load_dwordx2 v[150:151], v2, s[24:25]
	s_add_u32 s22, s22, 0x20000
	s_addc_u32 s23, s23, 0
	s_add_u32 s24, s24, 0x200
	s_addc_u32 s25, s25, 0
	s_waitcnt vmcnt(45)
	v_cvt_pk_bf16_f32 v44, v8, v9
	global_store_dword v42, v44, s[26:27]
	v_pk_fma_f32 v[8:9], v[8:9], v[152:153], v[120:121]
	s_add_u32 s26, s26, 0x10000
	s_addc_u32 s27, s27, 0
	global_load_dwordx2 v[120:121], v6, s[22:23]
	global_load_dwordx2 v[152:153], v2, s[24:25]
	s_add_u32 s22, s22, 0x20000
	s_addc_u32 s23, s23, 0
	s_add_u32 s24, s24, 0x200
	s_addc_u32 s25, s25, 0
	s_waitcnt vmcnt(45)
	v_cvt_pk_bf16_f32 v43, v8, v9
	global_store_dword v42, v43, s[26:27]
	v_pk_fma_f32 v[8:9], v[8:9], v[154:155], v[122:123]
	s_add_u32 s26, s26, 0x10000
	s_addc_u32 s27, s27, 0
	global_load_dwordx2 v[122:123], v6, s[22:23]
	global_load_dwordx2 v[154:155], v2, s[24:25]
	s_add_u32 s22, s22, 0x20000
	s_addc_u32 s23, s23, 0
	s_add_u32 s24, s24, 0x200
	s_addc_u32 s25, s25, 0
	s_waitcnt vmcnt(45)
	v_cvt_pk_bf16_f32 v44, v8, v9
	global_store_dword v42, v44, s[26:27]
	v_pk_fma_f32 v[8:9], v[8:9], v[156:157], v[124:125]
	s_add_u32 s26, s26, 0x10000
	s_addc_u32 s27, s27, 0
	global_load_dwordx2 v[124:125], v6, s[22:23]
	global_load_dwordx2 v[156:157], v2, s[24:25]
	s_add_u32 s22, s22, 0x20000
	s_addc_u32 s23, s23, 0
	s_add_u32 s24, s24, 0x200
	s_addc_u32 s25, s25, 0
	s_waitcnt vmcnt(45)
	v_cvt_pk_bf16_f32 v43, v8, v9
	global_store_dword v42, v43, s[26:27]
	v_pk_fma_f32 v[8:9], v[8:9], v[158:159], v[126:127]
	s_add_u32 s26, s26, 0x10000
	s_addc_u32 s27, s27, 0
	global_load_dwordx2 v[126:127], v6, s[22:23]
	global_load_dwordx2 v[158:159], v2, s[24:25]
	s_add_u32 s22, s22, 0x20000
	s_addc_u32 s23, s23, 0
	s_add_u32 s24, s24, 0x200
	s_addc_u32 s25, s25, 0
	s_waitcnt vmcnt(45)
	v_cvt_pk_bf16_f32 v44, v8, v9
	global_store_dword v42, v44, s[26:27]
	v_pk_fma_f32 v[8:9], v[8:9], v[160:161], v[128:129]
	s_add_u32 s26, s26, 0x10000
	s_addc_u32 s27, s27, 0
	global_load_dwordx2 v[128:129], v6, s[22:23]
	global_load_dwordx2 v[160:161], v2, s[24:25]
	s_add_u32 s22, s22, 0x20000
	s_addc_u32 s23, s23, 0
	s_add_u32 s24, s24, 0x200
	s_addc_u32 s25, s25, 0
	s_waitcnt vmcnt(45)
	v_cvt_pk_bf16_f32 v43, v8, v9
	global_store_dword v42, v43, s[26:27]
	v_pk_fma_f32 v[8:9], v[8:9], v[162:163], v[130:131]
	s_add_u32 s26, s26, 0x10000
	s_addc_u32 s27, s27, 0
	global_load_dwordx2 v[130:131], v6, s[22:23]
	global_load_dwordx2 v[162:163], v2, s[24:25]
	s_add_u32 s22, s22, 0x20000
	s_addc_u32 s23, s23, 0
	s_add_u32 s24, s24, 0x200
	s_addc_u32 s25, s25, 0
	s_waitcnt vmcnt(45)
	v_cvt_pk_bf16_f32 v44, v8, v9
	global_store_dword v42, v44, s[26:27]
	v_pk_fma_f32 v[8:9], v[8:9], v[164:165], v[132:133]
	s_add_u32 s26, s26, 0x10000
	s_addc_u32 s27, s27, 0
	global_load_dwordx2 v[132:133], v6, s[22:23]
	global_load_dwordx2 v[164:165], v2, s[24:25]
	s_add_u32 s22, s22, 0x20000
	s_addc_u32 s23, s23, 0
	s_add_u32 s24, s24, 0x200
	s_addc_u32 s25, s25, 0
	s_waitcnt vmcnt(45)
	v_cvt_pk_bf16_f32 v43, v8, v9
	global_store_dword v42, v43, s[26:27]
	v_pk_fma_f32 v[8:9], v[8:9], v[166:167], v[134:135]
	s_add_u32 s26, s26, 0x10000
	s_addc_u32 s27, s27, 0
	global_load_dwordx2 v[134:135], v6, s[22:23]
	global_load_dwordx2 v[166:167], v2, s[24:25]
	s_add_u32 s22, s22, 0x20000
	s_addc_u32 s23, s23, 0
	s_add_u32 s24, s24, 0x200
	s_addc_u32 s25, s25, 0
	s_waitcnt vmcnt(45)
	v_cvt_pk_bf16_f32 v44, v8, v9
	global_store_dword v42, v44, s[26:27]
	v_pk_fma_f32 v[8:9], v[8:9], v[168:169], v[136:137]
	s_add_u32 s26, s26, 0x10000
	s_addc_u32 s27, s27, 0
	global_load_dwordx2 v[136:137], v6, s[22:23]
	global_load_dwordx2 v[168:169], v2, s[24:25]
	s_add_u32 s22, s22, 0x20000
	s_addc_u32 s23, s23, 0
	s_add_u32 s24, s24, 0x200
	s_addc_u32 s25, s25, 0
	s_waitcnt vmcnt(45)
	v_cvt_pk_bf16_f32 v43, v8, v9
	global_store_dword v42, v43, s[26:27]
	v_pk_fma_f32 v[8:9], v[8:9], v[138:139], v[106:107]
	s_add_u32 s26, s26, 0x10000
	s_addc_u32 s27, s27, 0
	global_load_dwordx2 v[106:107], v6, s[22:23]
	global_load_dwordx2 v[138:139], v2, s[24:25]
	s_add_u32 s22, s22, 0x20000
	s_addc_u32 s23, s23, 0
	s_add_u32 s24, s24, 0x200
	s_addc_u32 s25, s25, 0
	s_waitcnt vmcnt(45)
	v_cvt_pk_bf16_f32 v44, v8, v9
	global_store_dword v42, v44, s[26:27]
	v_pk_fma_f32 v[8:9], v[8:9], v[140:141], v[108:109]
	s_add_u32 s26, s26, 0x10000
	s_addc_u32 s27, s27, 0
	global_load_dwordx2 v[108:109], v6, s[22:23]
	global_load_dwordx2 v[140:141], v2, s[24:25]
	s_add_u32 s22, s22, 0x20000
	s_addc_u32 s23, s23, 0
	s_add_u32 s24, s24, 0x200
	s_addc_u32 s25, s25, 0
	s_waitcnt vmcnt(45)
	v_cvt_pk_bf16_f32 v43, v8, v9
	global_store_dword v42, v43, s[26:27]
	v_pk_fma_f32 v[8:9], v[8:9], v[142:143], v[110:111]
	s_add_u32 s26, s26, 0x10000
	s_addc_u32 s27, s27, 0
	global_load_dwordx2 v[110:111], v6, s[22:23]
	global_load_dwordx2 v[142:143], v2, s[24:25]
	s_add_u32 s22, s22, 0x20000
	s_addc_u32 s23, s23, 0
	s_add_u32 s24, s24, 0x200
	s_addc_u32 s25, s25, 0
	s_waitcnt vmcnt(45)
	v_cvt_pk_bf16_f32 v44, v8, v9
	global_store_dword v42, v44, s[26:27]
	v_pk_fma_f32 v[8:9], v[8:9], v[144:145], v[112:113]
	s_add_u32 s26, s26, 0x10000
	s_addc_u32 s27, s27, 0
	global_load_dwordx2 v[112:113], v6, s[22:23]
	global_load_dwordx2 v[144:145], v2, s[24:25]
	s_add_u32 s22, s22, 0x20000
	s_addc_u32 s23, s23, 0
	s_add_u32 s24, s24, 0x200
	s_addc_u32 s25, s25, 0
	s_waitcnt vmcnt(45)
	v_cvt_pk_bf16_f32 v43, v8, v9
	global_store_dword v42, v43, s[26:27]
	v_pk_fma_f32 v[8:9], v[8:9], v[146:147], v[114:115]
	s_add_u32 s26, s26, 0x10000
	s_addc_u32 s27, s27, 0
	global_load_dwordx2 v[114:115], v6, s[22:23]
	global_load_dwordx2 v[146:147], v2, s[24:25]
	s_add_u32 s22, s22, 0x20000
	s_addc_u32 s23, s23, 0
	s_add_u32 s24, s24, 0x200
	s_addc_u32 s25, s25, 0
	s_waitcnt vmcnt(45)
	v_cvt_pk_bf16_f32 v44, v8, v9
	global_store_dword v42, v44, s[26:27]
	v_pk_fma_f32 v[8:9], v[8:9], v[148:149], v[116:117]
	s_add_u32 s26, s26, 0x10000
	s_addc_u32 s27, s27, 0
	global_load_dwordx2 v[116:117], v6, s[22:23]
	global_load_dwordx2 v[148:149], v2, s[24:25]
	s_add_u32 s22, s22, 0x20000
	s_addc_u32 s23, s23, 0
	s_add_u32 s24, s24, 0x200
	s_addc_u32 s25, s25, 0
	s_waitcnt vmcnt(45)
	v_cvt_pk_bf16_f32 v43, v8, v9
	global_store_dword v42, v43, s[26:27]
	v_pk_fma_f32 v[8:9], v[8:9], v[150:151], v[118:119]
	s_add_u32 s26, s26, 0x10000
	s_addc_u32 s27, s27, 0
	global_load_dwordx2 v[118:119], v6, s[22:23]
	global_load_dwordx2 v[150:151], v2, s[24:25]
	s_add_u32 s22, s22, 0x20000
	s_addc_u32 s23, s23, 0
	s_add_u32 s24, s24, 0x200
	s_addc_u32 s25, s25, 0
	s_waitcnt vmcnt(45)
	v_cvt_pk_bf16_f32 v44, v8, v9
	global_store_dword v42, v44, s[26:27]
	v_pk_fma_f32 v[8:9], v[8:9], v[152:153], v[120:121]
	s_add_u32 s26, s26, 0x10000
	s_addc_u32 s27, s27, 0
	global_load_dwordx2 v[120:121], v6, s[22:23]
	global_load_dwordx2 v[152:153], v2, s[24:25]
	s_add_u32 s22, s22, 0x20000
	s_addc_u32 s23, s23, 0
	s_add_u32 s24, s24, 0x200
	s_addc_u32 s25, s25, 0
	s_waitcnt vmcnt(45)
	v_cvt_pk_bf16_f32 v43, v8, v9
	global_store_dword v42, v43, s[26:27]
	v_pk_fma_f32 v[8:9], v[8:9], v[154:155], v[122:123]
	s_add_u32 s26, s26, 0x10000
	s_addc_u32 s27, s27, 0
	global_load_dwordx2 v[122:123], v6, s[22:23]
	global_load_dwordx2 v[154:155], v2, s[24:25]
	s_add_u32 s22, s22, 0x20000
	s_addc_u32 s23, s23, 0
	s_add_u32 s24, s24, 0x200
	s_addc_u32 s25, s25, 0
	s_waitcnt vmcnt(45)
	v_cvt_pk_bf16_f32 v44, v8, v9
	global_store_dword v42, v44, s[26:27]
	v_pk_fma_f32 v[8:9], v[8:9], v[156:157], v[124:125]
	s_add_u32 s26, s26, 0x10000
	s_addc_u32 s27, s27, 0
	global_load_dwordx2 v[124:125], v6, s[22:23]
	global_load_dwordx2 v[156:157], v2, s[24:25]
	s_add_u32 s22, s22, 0x20000
	s_addc_u32 s23, s23, 0
	s_add_u32 s24, s24, 0x200
	s_addc_u32 s25, s25, 0
	s_waitcnt vmcnt(45)
	v_cvt_pk_bf16_f32 v43, v8, v9
	global_store_dword v42, v43, s[26:27]
	v_pk_fma_f32 v[8:9], v[8:9], v[158:159], v[126:127]
	s_add_u32 s26, s26, 0x10000
	s_addc_u32 s27, s27, 0
	global_load_dwordx2 v[126:127], v6, s[22:23]
	global_load_dwordx2 v[158:159], v2, s[24:25]
	s_add_u32 s22, s22, 0x20000
	s_addc_u32 s23, s23, 0
	s_add_u32 s24, s24, 0x200
	s_addc_u32 s25, s25, 0
	s_waitcnt vmcnt(45)
	v_cvt_pk_bf16_f32 v44, v8, v9
	global_store_dword v42, v44, s[26:27]
	v_pk_fma_f32 v[8:9], v[8:9], v[160:161], v[128:129]
	s_add_u32 s26, s26, 0x10000
	s_addc_u32 s27, s27, 0
	global_load_dwordx2 v[128:129], v6, s[22:23]
	global_load_dwordx2 v[160:161], v2, s[24:25]
	s_add_u32 s22, s22, 0x20000
	s_addc_u32 s23, s23, 0
	s_add_u32 s24, s24, 0x200
	s_addc_u32 s25, s25, 0
	s_waitcnt vmcnt(45)
	v_cvt_pk_bf16_f32 v43, v8, v9
	global_store_dword v42, v43, s[26:27]
	v_pk_fma_f32 v[8:9], v[8:9], v[162:163], v[130:131]
	s_add_u32 s26, s26, 0x10000
	s_addc_u32 s27, s27, 0
	global_load_dwordx2 v[130:131], v6, s[22:23]
	global_load_dwordx2 v[162:163], v2, s[24:25]
	s_add_u32 s22, s22, 0x20000
	s_addc_u32 s23, s23, 0
	s_add_u32 s24, s24, 0x200
	s_addc_u32 s25, s25, 0
	s_waitcnt vmcnt(45)
	v_cvt_pk_bf16_f32 v44, v8, v9
	global_store_dword v42, v44, s[26:27]
	v_pk_fma_f32 v[8:9], v[8:9], v[164:165], v[132:133]
	s_add_u32 s26, s26, 0x10000
	s_addc_u32 s27, s27, 0
	global_load_dwordx2 v[132:133], v6, s[22:23]
	global_load_dwordx2 v[164:165], v2, s[24:25]
	s_add_u32 s22, s22, 0x20000
	s_addc_u32 s23, s23, 0
	s_add_u32 s24, s24, 0x200
	s_addc_u32 s25, s25, 0
	s_waitcnt vmcnt(45)
	v_cvt_pk_bf16_f32 v43, v8, v9
	global_store_dword v42, v43, s[26:27]
	v_pk_fma_f32 v[8:9], v[8:9], v[166:167], v[134:135]
	s_add_u32 s26, s26, 0x10000
	s_addc_u32 s27, s27, 0
	global_load_dwordx2 v[134:135], v6, s[22:23]
	global_load_dwordx2 v[166:167], v2, s[24:25]
	s_add_u32 s22, s22, 0x20000
	s_addc_u32 s23, s23, 0
	s_add_u32 s24, s24, 0x200
	s_addc_u32 s25, s25, 0
	s_waitcnt vmcnt(45)
	v_cvt_pk_bf16_f32 v44, v8, v9
	global_store_dword v42, v44, s[26:27]
	v_pk_fma_f32 v[8:9], v[8:9], v[168:169], v[136:137]
	s_add_u32 s26, s26, 0x10000
	s_addc_u32 s27, s27, 0
	global_load_dwordx2 v[136:137], v6, s[22:23]
	global_load_dwordx2 v[168:169], v2, s[24:25]
	s_add_u32 s22, s22, 0x20000
	s_addc_u32 s23, s23, 0
	s_add_u32 s24, s24, 0x200
	s_addc_u32 s25, s25, 0
	s_waitcnt vmcnt(45)
	v_cvt_pk_bf16_f32 v43, v8, v9
	global_store_dword v42, v43, s[26:27]
	v_pk_fma_f32 v[8:9], v[8:9], v[138:139], v[106:107]
	s_add_u32 s26, s26, 0x10000
	s_addc_u32 s27, s27, 0
	s_waitcnt vmcnt(43)
	v_cvt_pk_bf16_f32 v44, v8, v9
	global_store_dword v42, v44, s[26:27]
	v_pk_fma_f32 v[8:9], v[8:9], v[140:141], v[108:109]
	s_add_u32 s26, s26, 0x10000
	s_addc_u32 s27, s27, 0
	s_waitcnt vmcnt(41)
	v_cvt_pk_bf16_f32 v43, v8, v9
	global_store_dword v42, v43, s[26:27]
	v_pk_fma_f32 v[8:9], v[8:9], v[142:143], v[110:111]
	s_add_u32 s26, s26, 0x10000
	s_addc_u32 s27, s27, 0
	s_waitcnt vmcnt(39)
	v_cvt_pk_bf16_f32 v44, v8, v9
	global_store_dword v42, v44, s[26:27]
	v_pk_fma_f32 v[8:9], v[8:9], v[144:145], v[112:113]
	s_add_u32 s26, s26, 0x10000
	s_addc_u32 s27, s27, 0
	s_waitcnt vmcnt(37)
	v_cvt_pk_bf16_f32 v43, v8, v9
	global_store_dword v42, v43, s[26:27]
	v_pk_fma_f32 v[8:9], v[8:9], v[146:147], v[114:115]
	s_add_u32 s26, s26, 0x10000
	s_addc_u32 s27, s27, 0
	s_waitcnt vmcnt(35)
	v_cvt_pk_bf16_f32 v44, v8, v9
	global_store_dword v42, v44, s[26:27]
	v_pk_fma_f32 v[8:9], v[8:9], v[148:149], v[116:117]
	s_add_u32 s26, s26, 0x10000
	s_addc_u32 s27, s27, 0
	s_waitcnt vmcnt(33)
	v_cvt_pk_bf16_f32 v43, v8, v9
	global_store_dword v42, v43, s[26:27]
	v_pk_fma_f32 v[8:9], v[8:9], v[150:151], v[118:119]
	s_add_u32 s26, s26, 0x10000
	s_addc_u32 s27, s27, 0
	s_waitcnt vmcnt(31)
	v_cvt_pk_bf16_f32 v44, v8, v9
	global_store_dword v42, v44, s[26:27]
	v_pk_fma_f32 v[8:9], v[8:9], v[152:153], v[120:121]
	s_add_u32 s26, s26, 0x10000
	s_addc_u32 s27, s27, 0
	s_waitcnt vmcnt(29)
	v_cvt_pk_bf16_f32 v43, v8, v9
	global_store_dword v42, v43, s[26:27]
	v_pk_fma_f32 v[8:9], v[8:9], v[154:155], v[122:123]
	s_add_u32 s26, s26, 0x10000
	s_addc_u32 s27, s27, 0
	s_waitcnt vmcnt(27)
	v_cvt_pk_bf16_f32 v44, v8, v9
	global_store_dword v42, v44, s[26:27]
	v_pk_fma_f32 v[8:9], v[8:9], v[156:157], v[124:125]
	s_add_u32 s26, s26, 0x10000
	s_addc_u32 s27, s27, 0
	s_waitcnt vmcnt(25)
	v_cvt_pk_bf16_f32 v43, v8, v9
	global_store_dword v42, v43, s[26:27]
	v_pk_fma_f32 v[8:9], v[8:9], v[158:159], v[126:127]
	s_add_u32 s26, s26, 0x10000
	s_addc_u32 s27, s27, 0
	s_waitcnt vmcnt(23)
	v_cvt_pk_bf16_f32 v44, v8, v9
	global_store_dword v42, v44, s[26:27]
	v_pk_fma_f32 v[8:9], v[8:9], v[160:161], v[128:129]
	s_add_u32 s26, s26, 0x10000
	s_addc_u32 s27, s27, 0
	s_waitcnt vmcnt(21)
	v_cvt_pk_bf16_f32 v43, v8, v9
	global_store_dword v42, v43, s[26:27]
	v_pk_fma_f32 v[8:9], v[8:9], v[162:163], v[130:131]
	s_add_u32 s26, s26, 0x10000
	s_addc_u32 s27, s27, 0
	s_waitcnt vmcnt(19)
	v_cvt_pk_bf16_f32 v44, v8, v9
	global_store_dword v42, v44, s[26:27]
	v_pk_fma_f32 v[8:9], v[8:9], v[164:165], v[132:133]
	s_add_u32 s26, s26, 0x10000
	s_addc_u32 s27, s27, 0
	s_waitcnt vmcnt(17)
	v_cvt_pk_bf16_f32 v43, v8, v9
	global_store_dword v42, v43, s[26:27]
	v_pk_fma_f32 v[8:9], v[8:9], v[166:167], v[134:135]
	s_add_u32 s26, s26, 0x10000
	s_addc_u32 s27, s27, 0
	s_waitcnt vmcnt(15)
	v_cvt_pk_bf16_f32 v44, v8, v9
	global_store_dword v42, v44, s[26:27]
	v_pk_fma_f32 v[8:9], v[8:9], v[168:169], v[136:137]
	s_add_u32 s26, s26, 0x10000
	s_addc_u32 s27, s27, 0
	v_add_u32_e32 v1, s15, v1
	v_cmp_lt_i32_e32 vcc, s20, v1
	s_or_b64 s[6:7], vcc, s[6:7]
	v_add_u32_e32 v10, s16, v10
	s_andn2_b64 exec, exec, s[6:7]
	s_cbranch_execnz .LBB0_517

.LBB0_1301:
	s_add_u32 s22, s92, 0x17000000
	s_addc_u32 s23, s93, 0
	s_add_u32 s24, s92, 0xc00000
	s_addc_u32 s25, s93, 0
	s_mov_b32 s26, s2
	s_mov_b32 s27, s3
	v_lshlrev_b32_e32 v42, 1, v4
	global_load_dwordx2 v[106:107], v6, s[22:23]
	global_load_dwordx2 v[138:139], v2, s[24:25]
	s_add_u32 s22, s22, 0x20000
	s_addc_u32 s23, s23, 0
	s_add_u32 s24, s24, 0x200
	s_addc_u32 s25, s25, 0
	global_load_dwordx2 v[108:109], v6, s[22:23]
	global_load_dwordx2 v[140:141], v2, s[24:25]
	s_add_u32 s22, s22, 0x20000
	s_addc_u32 s23, s23, 0
	s_add_u32 s24, s24, 0x200
	s_addc_u32 s25, s25, 0
	global_load_dwordx2 v[110:111], v6, s[22:23]
	global_load_dwordx2 v[142:143], v2, s[24:25]
	s_add_u32 s22, s22, 0x20000
	s_addc_u32 s23, s23, 0
	s_add_u32 s24, s24, 0x200
	s_addc_u32 s25, s25, 0
	global_load_dwordx2 v[112:113], v6, s[22:23]
	global_load_dwordx2 v[144:145], v2, s[24:25]
	s_add_u32 s22, s22, 0x20000
	s_addc_u32 s23, s23, 0
	s_add_u32 s24, s24, 0x200
	s_addc_u32 s25, s25, 0
	global_load_dwordx2 v[114:115], v6, s[22:23]
	global_load_dwordx2 v[146:147], v2, s[24:25]
	s_add_u32 s22, s22, 0x20000
	s_addc_u32 s23, s23, 0
	s_add_u32 s24, s24, 0x200
	s_addc_u32 s25, s25, 0
	global_load_dwordx2 v[116:117], v6, s[22:23]
	global_load_dwordx2 v[148:149], v2, s[24:25]
	s_add_u32 s22, s22, 0x20000
	s_addc_u32 s23, s23, 0
	s_add_u32 s24, s24, 0x200
	s_addc_u32 s25, s25, 0
	global_load_dwordx2 v[118:119], v6, s[22:23]
	global_load_dwordx2 v[150:151], v2, s[24:25]
	s_add_u32 s22, s22, 0x20000
	s_addc_u32 s23, s23, 0
	s_add_u32 s24, s24, 0x200
	s_addc_u32 s25, s25, 0
	global_load_dwordx2 v[120:121], v6, s[22:23]
	global_load_dwordx2 v[152:153], v2, s[24:25]
	s_add_u32 s22, s22, 0x20000
	s_addc_u32 s23, s23, 0
	s_add_u32 s24, s24, 0x200
	s_addc_u32 s25, s25, 0
	global_load_dwordx2 v[122:123], v6, s[22:23]
	global_load_dwordx2 v[154:155], v2, s[24:25]
	s_add_u32 s22, s22, 0x20000
	s_addc_u32 s23, s23, 0
	s_add_u32 s24, s24, 0x200
	s_addc_u32 s25, s25, 0
	global_load_dwordx2 v[124:125], v6, s[22:23]
	global_load_dwordx2 v[156:157], v2, s[24:25]
	s_add_u32 s22, s22, 0x20000
	s_addc_u32 s23, s23, 0
	s_add_u32 s24, s24, 0x200
	s_addc_u32 s25, s25, 0
	global_load_dwordx2 v[126:127], v6, s[22:23]
	global_load_dwordx2 v[158:159], v2, s[24:25]
	s_add_u32 s22, s22, 0x20000
	s_addc_u32 s23, s23, 0
	s_add_u32 s24, s24, 0x200
	s_addc_u32 s25, s25, 0
	global_load_dwordx2 v[128:129], v6, s[22:23]
	global_load_dwordx2 v[160:161], v2, s[24:25]
	s_add_u32 s22, s22, 0x20000
	s_addc_u32 s23, s23, 0
	s_add_u32 s24, s24, 0x200
	s_addc_u32 s25, s25, 0
	global_load_dwordx2 v[130:131], v6, s[22:23]
	global_load_dwordx2 v[162:163], v2, s[24:25]
	s_add_u32 s22, s22, 0x20000
	s_addc_u32 s23, s23, 0
	s_add_u32 s24, s24, 0x200
	s_addc_u32 s25, s25, 0
	global_load_dwordx2 v[132:133], v6, s[22:23]
	global_load_dwordx2 v[164:165], v2, s[24:25]
	s_add_u32 s22, s22, 0x20000
	s_addc_u32 s23, s23, 0
	s_add_u32 s24, s24, 0x200
	s_addc_u32 s25, s25, 0
	global_load_dwordx2 v[134:135], v6, s[22:23]
	global_load_dwordx2 v[166:167], v2, s[24:25]
	s_add_u32 s22, s22, 0x20000
	s_addc_u32 s23, s23, 0
	s_add_u32 s24, s24, 0x200
	s_addc_u32 s25, s25, 0
	global_load_dwordx2 v[136:137], v6, s[22:23]
	global_load_dwordx2 v[168:169], v2, s[24:25]
	s_add_u32 s22, s22, 0x20000
	s_addc_u32 s23, s23, 0
	s_add_u32 s24, s24, 0x200
	s_addc_u32 s25, s25, 0
	s_waitcnt vmcnt(30)
	v_cvt_pk_bf16_f32 v43, v8, v9
	global_store_dword v42, v43, s[26:27]
	v_pk_fma_f32 v[8:9], v[8:9], v[138:139], v[106:107]
	s_add_u32 s26, s26, 0x10000
	s_addc_u32 s27, s27, 0
	global_load_dwordx2 v[106:107], v6, s[22:23]
	global_load_dwordx2 v[138:139], v2, s[24:25]
	s_add_u32 s22, s22, 0x20000
	s_addc_u32 s23, s23, 0
	s_add_u32 s24, s24, 0x200
	s_addc_u32 s25, s25, 0
	s_waitcnt vmcnt(31)
	v_cvt_pk_bf16_f32 v44, v8, v9
	global_store_dword v42, v44, s[26:27]
	v_pk_fma_f32 v[8:9], v[8:9], v[140:141], v[108:109]
	s_add_u32 s26, s26, 0x10000
	s_addc_u32 s27, s27, 0
	global_load_dwordx2 v[108:109], v6, s[22:23]
	global_load_dwordx2 v[140:141], v2, s[24:25]
	s_add_u32 s22, s22, 0x20000
	s_addc_u32 s23, s23, 0
	s_add_u32 s24, s24, 0x200
	s_addc_u32 s25, s25, 0
	s_waitcnt vmcnt(32)
	v_cvt_pk_bf16_f32 v43, v8, v9
	global_store_dword v42, v43, s[26:27]
	v_pk_fma_f32 v[8:9], v[8:9], v[142:143], v[110:111]
	s_add_u32 s26, s26, 0x10000
	s_addc_u32 s27, s27, 0
	global_load_dwordx2 v[110:111], v6, s[22:23]
	global_load_dwordx2 v[142:143], v2, s[24:25]
	s_add_u32 s22, s22, 0x20000
	s_addc_u32 s23, s23, 0
	s_add_u32 s24, s24, 0x200
	s_addc_u32 s25, s25, 0
	s_waitcnt vmcnt(33)
	v_cvt_pk_bf16_f32 v44, v8, v9
	global_store_dword v42, v44, s[26:27]
	v_pk_fma_f32 v[8:9], v[8:9], v[144:145], v[112:113]
	s_add_u32 s26, s26, 0x10000
	s_addc_u32 s27, s27, 0
	global_load_dwordx2 v[112:113], v6, s[22:23]
	global_load_dwordx2 v[144:145], v2, s[24:25]
	s_add_u32 s22, s22, 0x20000
	s_addc_u32 s23, s23, 0
	s_add_u32 s24, s24, 0x200
	s_addc_u32 s25, s25, 0
	s_waitcnt vmcnt(34)
	v_cvt_pk_bf16_f32 v43, v8, v9
	global_store_dword v42, v43, s[26:27]
	v_pk_fma_f32 v[8:9], v[8:9], v[146:147], v[114:115]
	s_add_u32 s26, s26, 0x10000
	s_addc_u32 s27, s27, 0
	global_load_dwordx2 v[114:115], v6, s[22:23]
	global_load_dwordx2 v[146:147], v2, s[24:25]
	s_add_u32 s22, s22, 0x20000
	s_addc_u32 s23, s23, 0
	s_add_u32 s24, s24, 0x200
	s_addc_u32 s25, s25, 0
	s_waitcnt vmcnt(35)
	v_cvt_pk_bf16_f32 v44, v8, v9
	global_store_dword v42, v44, s[26:27]
	v_pk_fma_f32 v[8:9], v[8:9], v[148:149], v[116:117]
	s_add_u32 s26, s26, 0x10000
	s_addc_u32 s27, s27, 0
	global_load_dwordx2 v[116:117], v6, s[22:23]
	global_load_dwordx2 v[148:149], v2, s[24:25]
	s_add_u32 s22, s22, 0x20000
	s_addc_u32 s23, s23, 0
	s_add_u32 s24, s24, 0x200
	s_addc_u32 s25, s25, 0
	s_waitcnt vmcnt(36)
	v_cvt_pk_bf16_f32 v43, v8, v9
	global_store_dword v42, v43, s[26:27]
	v_pk_fma_f32 v[8:9], v[8:9], v[150:151], v[118:119]
	s_add_u32 s26, s26, 0x10000
	s_addc_u32 s27, s27, 0
	global_load_dwordx2 v[118:119], v6, s[22:23]
	global_load_dwordx2 v[150:151], v2, s[24:25]
	s_add_u32 s22, s22, 0x20000
	s_addc_u32 s23, s23, 0
	s_add_u32 s24, s24, 0x200
	s_addc_u32 s25, s25, 0
	s_waitcnt vmcnt(37)
	v_cvt_pk_bf16_f32 v44, v8, v9
	global_store_dword v42, v44, s[26:27]
	v_pk_fma_f32 v[8:9], v[8:9], v[152:153], v[120:121]
	s_add_u32 s26, s26, 0x10000
	s_addc_u32 s27, s27, 0
	global_load_dwordx2 v[120:121], v6, s[22:23]
	global_load_dwordx2 v[152:153], v2, s[24:25]
	s_add_u32 s22, s22, 0x20000
	s_addc_u32 s23, s23, 0
	s_add_u32 s24, s24, 0x200
	s_addc_u32 s25, s25, 0
	s_waitcnt vmcnt(38)
	v_cvt_pk_bf16_f32 v43, v8, v9
	global_store_dword v42, v43, s[26:27]
	v_pk_fma_f32 v[8:9], v[8:9], v[154:155], v[122:123]
	s_add_u32 s26, s26, 0x10000
	s_addc_u32 s27, s27, 0
	global_load_dwordx2 v[122:123], v6, s[22:23]
	global_load_dwordx2 v[154:155], v2, s[24:25]
	s_add_u32 s22, s22, 0x20000
	s_addc_u32 s23, s23, 0
	s_add_u32 s24, s24, 0x200
	s_addc_u32 s25, s25, 0
	s_waitcnt vmcnt(39)
	v_cvt_pk_bf16_f32 v44, v8, v9
	global_store_dword v42, v44, s[26:27]
	v_pk_fma_f32 v[8:9], v[8:9], v[156:157], v[124:125]
	s_add_u32 s26, s26, 0x10000
	s_addc_u32 s27, s27, 0
	global_load_dwordx2 v[124:125], v6, s[22:23]
	global_load_dwordx2 v[156:157], v2, s[24:25]
	s_add_u32 s22, s22, 0x20000
	s_addc_u32 s23, s23, 0
	s_add_u32 s24, s24, 0x200
	s_addc_u32 s25, s25, 0
	s_waitcnt vmcnt(40)
	v_cvt_pk_bf16_f32 v43, v8, v9
	global_store_dword v42, v43, s[26:27]
	v_pk_fma_f32 v[8:9], v[8:9], v[158:159], v[126:127]
	s_add_u32 s26, s26, 0x10000
	s_addc_u32 s27, s27, 0
	global_load_dwordx2 v[126:127], v6, s[22:23]
	global_load_dwordx2 v[158:159], v2, s[24:25]
	s_add_u32 s22, s22, 0x20000
	s_addc_u32 s23, s23, 0
	s_add_u32 s24, s24, 0x200
	s_addc_u32 s25, s25, 0
	s_waitcnt vmcnt(41)
	v_cvt_pk_bf16_f32 v44, v8, v9
	global_store_dword v42, v44, s[26:27]
	v_pk_fma_f32 v[8:9], v[8:9], v[160:161], v[128:129]
	s_add_u32 s26, s26, 0x10000
	s_addc_u32 s27, s27, 0
	global_load_dwordx2 v[128:129], v6, s[22:23]
	global_load_dwordx2 v[160:161], v2, s[24:25]
	s_add_u32 s22, s22, 0x20000
	s_addc_u32 s23, s23, 0
	s_add_u32 s24, s24, 0x200
	s_addc_u32 s25, s25, 0
	s_waitcnt vmcnt(42)
	v_cvt_pk_bf16_f32 v43, v8, v9
	global_store_dword v42, v43, s[26:27]
	v_pk_fma_f32 v[8:9], v[8:9], v[162:163], v[130:131]
	s_add_u32 s26, s26, 0x10000
	s_addc_u32 s27, s27, 0
	global_load_dwordx2 v[130:131], v6, s[22:23]
	global_load_dwordx2 v[162:163], v2, s[24:25]
	s_add_u32 s22, s22, 0x20000
	s_addc_u32 s23, s23, 0
	s_add_u32 s24, s24, 0x200
	s_addc_u32 s25, s25, 0
	s_waitcnt vmcnt(43)
	v_cvt_pk_bf16_f32 v44, v8, v9
	global_store_dword v42, v44, s[26:27]
	v_pk_fma_f32 v[8:9], v[8:9], v[164:165], v[132:133]
	s_add_u32 s26, s26, 0x10000
	s_addc_u32 s27, s27, 0
	global_load_dwordx2 v[132:133], v6, s[22:23]
	global_load_dwordx2 v[164:165], v2, s[24:25]
	s_add_u32 s22, s22, 0x20000
	s_addc_u32 s23, s23, 0
	s_add_u32 s24, s24, 0x200
	s_addc_u32 s25, s25, 0
	s_waitcnt vmcnt(44)
	v_cvt_pk_bf16_f32 v43, v8, v9
	global_store_dword v42, v43, s[26:27]
	v_pk_fma_f32 v[8:9], v[8:9], v[166:167], v[134:135]
	s_add_u32 s26, s26, 0x10000
	s_addc_u32 s27, s27, 0
	global_load_dwordx2 v[134:135], v6, s[22:23]
	global_load_dwordx2 v[166:167], v2, s[24:25]
	s_add_u32 s22, s22, 0x20000
	s_addc_u32 s23, s23, 0
	s_add_u32 s24, s24, 0x200
	s_addc_u32 s25, s25, 0
	s_waitcnt vmcnt(45)
	v_cvt_pk_bf16_f32 v44, v8, v9
	global_store_dword v42, v44, s[26:27]
	v_pk_fma_f32 v[8:9], v[8:9], v[168:169], v[136:137]
	s_add_u32 s26, s26, 0x10000
	s_addc_u32 s27, s27, 0
	global_load_dwordx2 v[136:137], v6, s[22:23]
	global_load_dwordx2 v[168:169], v2, s[24:25]
	s_add_u32 s22, s22, 0x20000
	s_addc_u32 s23, s23, 0
	s_add_u32 s24, s24, 0x200
	s_addc_u32 s25, s25, 0
	s_waitcnt vmcnt(45)
	v_cvt_pk_bf16_f32 v43, v8, v9
	global_store_dword v42, v43, s[26:27]
	v_pk_fma_f32 v[8:9], v[8:9], v[138:139], v[106:107]
	s_add_u32 s26, s26, 0x10000
	s_addc_u32 s27, s27, 0
	global_load_dwordx2 v[106:107], v6, s[22:23]
	global_load_dwordx2 v[138:139], v2, s[24:25]
	s_add_u32 s22, s22, 0x20000
	s_addc_u32 s23, s23, 0
	s_add_u32 s24, s24, 0x200
	s_addc_u32 s25, s25, 0
	s_waitcnt vmcnt(45)
	v_cvt_pk_bf16_f32 v44, v8, v9
	global_store_dword v42, v44, s[26:27]
	v_pk_fma_f32 v[8:9], v[8:9], v[140:141], v[108:109]
	s_add_u32 s26, s26, 0x10000
	s_addc_u32 s27, s27, 0
	global_load_dwordx2 v[108:109], v6, s[22:23]
	global_load_dwordx2 v[140:141], v2, s[24:25]
	s_add_u32 s22, s22, 0x20000
	s_addc_u32 s23, s23, 0
	s_add_u32 s24, s24, 0x200
	s_addc_u32 s25, s25, 0
	s_waitcnt vmcnt(45)
	v_cvt_pk_bf16_f32 v43, v8, v9
	global_store_dword v42, v43, s[26:27]
	v_pk_fma_f32 v[8:9], v[8:9], v[142:143], v[110:111]
	s_add_u32 s26, s26, 0x10000
	s_addc_u32 s27, s27, 0
	global_load_dwordx2 v[110:111], v6, s[22:23]
	global_load_dwordx2 v[142:143], v2, s[24:25]
	s_add_u32 s22, s22, 0x20000
	s_addc_u32 s23, s23, 0
	s_add_u32 s24, s24, 0x200
	s_addc_u32 s25, s25, 0
	s_waitcnt vmcnt(45)
	v_cvt_pk_bf16_f32 v44, v8, v9
	global_store_dword v42, v44, s[26:27]
	v_pk_fma_f32 v[8:9], v[8:9], v[144:145], v[112:113]
	s_add_u32 s26, s26, 0x10000
	s_addc_u32 s27, s27, 0
	global_load_dwordx2 v[112:113], v6, s[22:23]
	global_load_dwordx2 v[144:145], v2, s[24:25]
	s_add_u32 s22, s22, 0x20000
	s_addc_u32 s23, s23, 0
	s_add_u32 s24, s24, 0x200
	s_addc_u32 s25, s25, 0
	s_waitcnt vmcnt(45)
	v_cvt_pk_bf16_f32 v43, v8, v9
	global_store_dword v42, v43, s[26:27]
	v_pk_fma_f32 v[8:9], v[8:9], v[146:147], v[114:115]
	s_add_u32 s26, s26, 0x10000
	s_addc_u32 s27, s27, 0
	global_load_dwordx2 v[114:115], v6, s[22:23]
	global_load_dwordx2 v[146:147], v2, s[24:25]
	s_add_u32 s22, s22, 0x20000
	s_addc_u32 s23, s23, 0
	s_add_u32 s24, s24, 0x200
	s_addc_u32 s25, s25, 0
	s_waitcnt vmcnt(45)
	v_cvt_pk_bf16_f32 v44, v8, v9
	global_store_dword v42, v44, s[26:27]
	v_pk_fma_f32 v[8:9], v[8:9], v[148:149], v[116:117]
	s_add_u32 s26, s26, 0x10000
	s_addc_u32 s27, s27, 0
	global_load_dwordx2 v[116:117], v6, s[22:23]
	global_load_dwordx2 v[148:149], v2, s[24:25]
	s_add_u32 s22, s22, 0x20000
	s_addc_u32 s23, s23, 0
	s_add_u32 s24, s24, 0x200
	s_addc_u32 s25, s25, 0
	s_waitcnt vmcnt(45)
	v_cvt_pk_bf16_f32 v43, v8, v9
	global_store_dword v42, v43, s[26:27]
	v_pk_fma_f32 v[8:9], v[8:9], v[150:151], v[118:119]
	s_add_u32 s26, s26, 0x10000
	s_addc_u32 s27, s27, 0
	global_load_dwordx2 v[118:119], v6, s[22:23]
	global_load_dwordx2 v[150:151], v2, s[24:25]
	s_add_u32 s22, s22, 0x20000
	s_addc_u32 s23, s23, 0
	s_add_u32 s24, s24, 0x200
	s_addc_u32 s25, s25, 0
	s_waitcnt vmcnt(45)
	v_cvt_pk_bf16_f32 v44, v8, v9
	global_store_dword v42, v44, s[26:27]
	v_pk_fma_f32 v[8:9], v[8:9], v[152:153], v[120:121]
	s_add_u32 s26, s26, 0x10000
	s_addc_u32 s27, s27, 0
	global_load_dwordx2 v[120:121], v6, s[22:23]
	global_load_dwordx2 v[152:153], v2, s[24:25]
	s_add_u32 s22, s22, 0x20000
	s_addc_u32 s23, s23, 0
	s_add_u32 s24, s24, 0x200
	s_addc_u32 s25, s25, 0
	s_waitcnt vmcnt(45)
	v_cvt_pk_bf16_f32 v43, v8, v9
	global_store_dword v42, v43, s[26:27]
	v_pk_fma_f32 v[8:9], v[8:9], v[154:155], v[122:123]
	s_add_u32 s26, s26, 0x10000
	s_addc_u32 s27, s27, 0
	global_load_dwordx2 v[122:123], v6, s[22:23]
	global_load_dwordx2 v[154:155], v2, s[24:25]
	s_add_u32 s22, s22, 0x20000
	s_addc_u32 s23, s23, 0
	s_add_u32 s24, s24, 0x200
	s_addc_u32 s25, s25, 0
	s_waitcnt vmcnt(45)
	v_cvt_pk_bf16_f32 v44, v8, v9
	global_store_dword v42, v44, s[26:27]
	v_pk_fma_f32 v[8:9], v[8:9], v[156:157], v[124:125]
	s_add_u32 s26, s26, 0x10000
	s_addc_u32 s27, s27, 0
	global_load_dwordx2 v[124:125], v6, s[22:23]
	global_load_dwordx2 v[156:157], v2, s[24:25]
	s_add_u32 s22, s22, 0x20000
	s_addc_u32 s23, s23, 0
	s_add_u32 s24, s24, 0x200
	s_addc_u32 s25, s25, 0
	s_waitcnt vmcnt(45)
	v_cvt_pk_bf16_f32 v43, v8, v9
	global_store_dword v42, v43, s[26:27]
	v_pk_fma_f32 v[8:9], v[8:9], v[158:159], v[126:127]
	s_add_u32 s26, s26, 0x10000
	s_addc_u32 s27, s27, 0
	global_load_dwordx2 v[126:127], v6, s[22:23]
	global_load_dwordx2 v[158:159], v2, s[24:25]
	s_add_u32 s22, s22, 0x20000
	s_addc_u32 s23, s23, 0
	s_add_u32 s24, s24, 0x200
	s_addc_u32 s25, s25, 0
	s_waitcnt vmcnt(45)
	v_cvt_pk_bf16_f32 v44, v8, v9
	global_store_dword v42, v44, s[26:27]
	v_pk_fma_f32 v[8:9], v[8:9], v[160:161], v[128:129]
	s_add_u32 s26, s26, 0x10000
	s_addc_u32 s27, s27, 0
	global_load_dwordx2 v[128:129], v6, s[22:23]
	global_load_dwordx2 v[160:161], v2, s[24:25]
	s_add_u32 s22, s22, 0x20000
	s_addc_u32 s23, s23, 0
	s_add_u32 s24, s24, 0x200
	s_addc_u32 s25, s25, 0
	s_waitcnt vmcnt(45)
	v_cvt_pk_bf16_f32 v43, v8, v9
	global_store_dword v42, v43, s[26:27]
	v_pk_fma_f32 v[8:9], v[8:9], v[162:163], v[130:131]
	s_add_u32 s26, s26, 0x10000
	s_addc_u32 s27, s27, 0
	global_load_dwordx2 v[130:131], v6, s[22:23]
	global_load_dwordx2 v[162:163], v2, s[24:25]
	s_add_u32 s22, s22, 0x20000
	s_addc_u32 s23, s23, 0
	s_add_u32 s24, s24, 0x200
	s_addc_u32 s25, s25, 0
	s_waitcnt vmcnt(45)
	v_cvt_pk_bf16_f32 v44, v8, v9
	global_store_dword v42, v44, s[26:27]
	v_pk_fma_f32 v[8:9], v[8:9], v[164:165], v[132:133]
	s_add_u32 s26, s26, 0x10000
	s_addc_u32 s27, s27, 0
	global_load_dwordx2 v[132:133], v6, s[22:23]
	global_load_dwordx2 v[164:165], v2, s[24:25]
	s_add_u32 s22, s22, 0x20000
	s_addc_u32 s23, s23, 0
	s_add_u32 s24, s24, 0x200
	s_addc_u32 s25, s25, 0
	s_waitcnt vmcnt(45)
	v_cvt_pk_bf16_f32 v43, v8, v9
	global_store_dword v42, v43, s[26:27]
	v_pk_fma_f32 v[8:9], v[8:9], v[166:167], v[134:135]
	s_add_u32 s26, s26, 0x10000
	s_addc_u32 s27, s27, 0
	global_load_dwordx2 v[134:135], v6, s[22:23]
	global_load_dwordx2 v[166:167], v2, s[24:25]
	s_add_u32 s22, s22, 0x20000
	s_addc_u32 s23, s23, 0
	s_add_u32 s24, s24, 0x200
	s_addc_u32 s25, s25, 0
	s_waitcnt vmcnt(45)
	v_cvt_pk_bf16_f32 v44, v8, v9
	global_store_dword v42, v44, s[26:27]
	v_pk_fma_f32 v[8:9], v[8:9], v[168:169], v[136:137]
	s_add_u32 s26, s26, 0x10000
	s_addc_u32 s27, s27, 0
	global_load_dwordx2 v[136:137], v6, s[22:23]
	global_load_dwordx2 v[168:169], v2, s[24:25]
	s_add_u32 s22, s22, 0x20000
	s_addc_u32 s23, s23, 0
	s_add_u32 s24, s24, 0x200
	s_addc_u32 s25, s25, 0
	s_waitcnt vmcnt(45)
	v_cvt_pk_bf16_f32 v43, v8, v9
	global_store_dword v42, v43, s[26:27]
	v_pk_fma_f32 v[8:9], v[8:9], v[138:139], v[106:107]
	s_add_u32 s26, s26, 0x10000
	s_addc_u32 s27, s27, 0
	global_load_dwordx2 v[106:107], v6, s[22:23]
	global_load_dwordx2 v[138:139], v2, s[24:25]
	s_add_u32 s22, s22, 0x20000
	s_addc_u32 s23, s23, 0
	s_add_u32 s24, s24, 0x200
	s_addc_u32 s25, s25, 0
	s_waitcnt vmcnt(45)
	v_cvt_pk_bf16_f32 v44, v8, v9
	global_store_dword v42, v44, s[26:27]
	v_pk_fma_f32 v[8:9], v[8:9], v[140:141], v[108:109]
	s_add_u32 s26, s26, 0x10000
	s_addc_u32 s27, s27, 0
	global_load_dwordx2 v[108:109], v6, s[22:23]
	global_load_dwordx2 v[140:141], v2, s[24:25]
	s_add_u32 s22, s22, 0x20000
	s_addc_u32 s23, s23, 0
	s_add_u32 s24, s24, 0x200
	s_addc_u32 s25, s25, 0
	s_waitcnt vmcnt(45)
	v_cvt_pk_bf16_f32 v43, v8, v9
	global_store_dword v42, v43, s[26:27]
	v_pk_fma_f32 v[8:9], v[8:9], v[142:143], v[110:111]
	s_add_u32 s26, s26, 0x10000
	s_addc_u32 s27, s27, 0
	global_load_dwordx2 v[110:111], v6, s[22:23]
	global_load_dwordx2 v[142:143], v2, s[24:25]
	s_add_u32 s22, s22, 0x20000
	s_addc_u32 s23, s23, 0
	s_add_u32 s24, s24, 0x200
	s_addc_u32 s25, s25, 0
	s_waitcnt vmcnt(45)
	v_cvt_pk_bf16_f32 v44, v8, v9
	global_store_dword v42, v44, s[26:27]
	v_pk_fma_f32 v[8:9], v[8:9], v[144:145], v[112:113]
	s_add_u32 s26, s26, 0x10000
	s_addc_u32 s27, s27, 0
	global_load_dwordx2 v[112:113], v6, s[22:23]
	global_load_dwordx2 v[144:145], v2, s[24:25]
	s_add_u32 s22, s22, 0x20000
	s_addc_u32 s23, s23, 0
	s_add_u32 s24, s24, 0x200
	s_addc_u32 s25, s25, 0
	s_waitcnt vmcnt(45)
	v_cvt_pk_bf16_f32 v43, v8, v9
	global_store_dword v42, v43, s[26:27]
	v_pk_fma_f32 v[8:9], v[8:9], v[146:147], v[114:115]
	s_add_u32 s26, s26, 0x10000
	s_addc_u32 s27, s27, 0
	global_load_dwordx2 v[114:115], v6, s[22:23]
	global_load_dwordx2 v[146:147], v2, s[24:25]
	s_add_u32 s22, s22, 0x20000
	s_addc_u32 s23, s23, 0
	s_add_u32 s24, s24, 0x200
	s_addc_u32 s25, s25, 0
	s_waitcnt vmcnt(45)
	v_cvt_pk_bf16_f32 v44, v8, v9
	global_store_dword v42, v44, s[26:27]
	v_pk_fma_f32 v[8:9], v[8:9], v[148:149], v[116:117]
	s_add_u32 s26, s26, 0x10000
	s_addc_u32 s27, s27, 0
	global_load_dwordx2 v[116:117], v6, s[22:23]
	global_load_dwordx2 v[148:149], v2, s[24:25]
	s_add_u32 s22, s22, 0x20000
	s_addc_u32 s23, s23, 0
	s_add_u32 s24, s24, 0x200
	s_addc_u32 s25, s25, 0
	s_waitcnt vmcnt(45)
	v_cvt_pk_bf16_f32 v43, v8, v9
	global_store_dword v42, v43, s[26:27]
	v_pk_fma_f32 v[8:9], v[8:9], v[150:151], v[118:119]
	s_add_u32 s26, s26, 0x10000
	s_addc_u32 s27, s27, 0
	global_load_dwordx2 v[118:119], v6, s[22:23]
	global_load_dwordx2 v[150:151], v2, s[24:25]
	s_add_u32 s22, s22, 0x20000
	s_addc_u32 s23, s23, 0
	s_add_u32 s24, s24, 0x200
	s_addc_u32 s25, s25, 0
	s_waitcnt vmcnt(45)
	v_cvt_pk_bf16_f32 v44, v8, v9
	global_store_dword v42, v44, s[26:27]
	v_pk_fma_f32 v[8:9], v[8:9], v[152:153], v[120:121]
	s_add_u32 s26, s26, 0x10000
	s_addc_u32 s27, s27, 0
	global_load_dwordx2 v[120:121], v6, s[22:23]
	global_load_dwordx2 v[152:153], v2, s[24:25]
	s_add_u32 s22, s22, 0x20000
	s_addc_u32 s23, s23, 0
	s_add_u32 s24, s24, 0x200
	s_addc_u32 s25, s25, 0
	s_waitcnt vmcnt(45)
	v_cvt_pk_bf16_f32 v43, v8, v9
	global_store_dword v42, v43, s[26:27]
	v_pk_fma_f32 v[8:9], v[8:9], v[154:155], v[122:123]
	s_add_u32 s26, s26, 0x10000
	s_addc_u32 s27, s27, 0
	global_load_dwordx2 v[122:123], v6, s[22:23]
	global_load_dwordx2 v[154:155], v2, s[24:25]
	s_add_u32 s22, s22, 0x20000
	s_addc_u32 s23, s23, 0
	s_add_u32 s24, s24, 0x200
	s_addc_u32 s25, s25, 0
	s_waitcnt vmcnt(45)
	v_cvt_pk_bf16_f32 v44, v8, v9
	global_store_dword v42, v44, s[26:27]
	v_pk_fma_f32 v[8:9], v[8:9], v[156:157], v[124:125]
	s_add_u32 s26, s26, 0x10000
	s_addc_u32 s27, s27, 0
	global_load_dwordx2 v[124:125], v6, s[22:23]
	global_load_dwordx2 v[156:157], v2, s[24:25]
	s_add_u32 s22, s22, 0x20000
	s_addc_u32 s23, s23, 0
	s_add_u32 s24, s24, 0x200
	s_addc_u32 s25, s25, 0
	s_waitcnt vmcnt(45)
	v_cvt_pk_bf16_f32 v43, v8, v9
	global_store_dword v42, v43, s[26:27]
	v_pk_fma_f32 v[8:9], v[8:9], v[158:159], v[126:127]
	s_add_u32 s26, s26, 0x10000
	s_addc_u32 s27, s27, 0
	global_load_dwordx2 v[126:127], v6, s[22:23]
	global_load_dwordx2 v[158:159], v2, s[24:25]
	s_add_u32 s22, s22, 0x20000
	s_addc_u32 s23, s23, 0
	s_add_u32 s24, s24, 0x200
	s_addc_u32 s25, s25, 0
	s_waitcnt vmcnt(45)
	v_cvt_pk_bf16_f32 v44, v8, v9
	global_store_dword v42, v44, s[26:27]
	v_pk_fma_f32 v[8:9], v[8:9], v[160:161], v[128:129]
	s_add_u32 s26, s26, 0x10000
	s_addc_u32 s27, s27, 0
	global_load_dwordx2 v[128:129], v6, s[22:23]
	global_load_dwordx2 v[160:161], v2, s[24:25]
	s_add_u32 s22, s22, 0x20000
	s_addc_u32 s23, s23, 0
	s_add_u32 s24, s24, 0x200
	s_addc_u32 s25, s25, 0
	s_waitcnt vmcnt(45)
	v_cvt_pk_bf16_f32 v43, v8, v9
	global_store_dword v42, v43, s[26:27]
	v_pk_fma_f32 v[8:9], v[8:9], v[162:163], v[130:131]
	s_add_u32 s26, s26, 0x10000
	s_addc_u32 s27, s27, 0
	global_load_dwordx2 v[130:131], v6, s[22:23]
	global_load_dwordx2 v[162:163], v2, s[24:25]
	s_add_u32 s22, s22, 0x20000
	s_addc_u32 s23, s23, 0
	s_add_u32 s24, s24, 0x200
	s_addc_u32 s25, s25, 0
	s_waitcnt vmcnt(45)
	v_cvt_pk_bf16_f32 v44, v8, v9
	global_store_dword v42, v44, s[26:27]
	v_pk_fma_f32 v[8:9], v[8:9], v[164:165], v[132:133]
	s_add_u32 s26, s26, 0x10000
	s_addc_u32 s27, s27, 0
	global_load_dwordx2 v[132:133], v6, s[22:23]
	global_load_dwordx2 v[164:165], v2, s[24:25]
	s_add_u32 s22, s22, 0x20000
	s_addc_u32 s23, s23, 0
	s_add_u32 s24, s24, 0x200
	s_addc_u32 s25, s25, 0
	s_waitcnt vmcnt(45)
	v_cvt_pk_bf16_f32 v43, v8, v9
	global_store_dword v42, v43, s[26:27]
	v_pk_fma_f32 v[8:9], v[8:9], v[166:167], v[134:135]
	s_add_u32 s26, s26, 0x10000
	s_addc_u32 s27, s27, 0
	global_load_dwordx2 v[134:135], v6, s[22:23]
	global_load_dwordx2 v[166:167], v2, s[24:25]
	s_add_u32 s22, s22, 0x20000
	s_addc_u32 s23, s23, 0
	s_add_u32 s24, s24, 0x200
	s_addc_u32 s25, s25, 0
	s_waitcnt vmcnt(45)
	v_cvt_pk_bf16_f32 v44, v8, v9
	global_store_dword v42, v44, s[26:27]
	v_pk_fma_f32 v[8:9], v[8:9], v[168:169], v[136:137]
	s_add_u32 s26, s26, 0x10000
	s_addc_u32 s27, s27, 0
	global_load_dwordx2 v[136:137], v6, s[22:23]
	global_load_dwordx2 v[168:169], v2, s[24:25]
	s_add_u32 s22, s22, 0x20000
	s_addc_u32 s23, s23, 0
	s_add_u32 s24, s24, 0x200
	s_addc_u32 s25, s25, 0
	s_waitcnt vmcnt(45)
	v_cvt_pk_bf16_f32 v43, v8, v9
	global_store_dword v42, v43, s[26:27]
	v_pk_fma_f32 v[8:9], v[8:9], v[138:139], v[106:107]
	s_add_u32 s26, s26, 0x10000
	s_addc_u32 s27, s27, 0
	s_waitcnt vmcnt(43)
	v_cvt_pk_bf16_f32 v44, v8, v9
	global_store_dword v42, v44, s[26:27]
	v_pk_fma_f32 v[8:9], v[8:9], v[140:141], v[108:109]
	s_add_u32 s26, s26, 0x10000
	s_addc_u32 s27, s27, 0
	s_waitcnt vmcnt(41)
	v_cvt_pk_bf16_f32 v43, v8, v9
	global_store_dword v42, v43, s[26:27]
	v_pk_fma_f32 v[8:9], v[8:9], v[142:143], v[110:111]
	s_add_u32 s26, s26, 0x10000
	s_addc_u32 s27, s27, 0
	s_waitcnt vmcnt(39)
	v_cvt_pk_bf16_f32 v44, v8, v9
	global_store_dword v42, v44, s[26:27]
	v_pk_fma_f32 v[8:9], v[8:9], v[144:145], v[112:113]
	s_add_u32 s26, s26, 0x10000
	s_addc_u32 s27, s27, 0
	s_waitcnt vmcnt(37)
	v_cvt_pk_bf16_f32 v43, v8, v9
	global_store_dword v42, v43, s[26:27]
	v_pk_fma_f32 v[8:9], v[8:9], v[146:147], v[114:115]
	s_add_u32 s26, s26, 0x10000
	s_addc_u32 s27, s27, 0
	s_waitcnt vmcnt(35)
	v_cvt_pk_bf16_f32 v44, v8, v9
	global_store_dword v42, v44, s[26:27]
	v_pk_fma_f32 v[8:9], v[8:9], v[148:149], v[116:117]
	s_add_u32 s26, s26, 0x10000
	s_addc_u32 s27, s27, 0
	s_waitcnt vmcnt(33)
	v_cvt_pk_bf16_f32 v43, v8, v9
	global_store_dword v42, v43, s[26:27]
	v_pk_fma_f32 v[8:9], v[8:9], v[150:151], v[118:119]
	s_add_u32 s26, s26, 0x10000
	s_addc_u32 s27, s27, 0
	s_waitcnt vmcnt(31)
	v_cvt_pk_bf16_f32 v44, v8, v9
	global_store_dword v42, v44, s[26:27]
	v_pk_fma_f32 v[8:9], v[8:9], v[152:153], v[120:121]
	s_add_u32 s26, s26, 0x10000
	s_addc_u32 s27, s27, 0
	s_waitcnt vmcnt(29)
	v_cvt_pk_bf16_f32 v43, v8, v9
	global_store_dword v42, v43, s[26:27]
	v_pk_fma_f32 v[8:9], v[8:9], v[154:155], v[122:123]
	s_add_u32 s26, s26, 0x10000
	s_addc_u32 s27, s27, 0
	s_waitcnt vmcnt(27)
	v_cvt_pk_bf16_f32 v44, v8, v9
	global_store_dword v42, v44, s[26:27]
	v_pk_fma_f32 v[8:9], v[8:9], v[156:157], v[124:125]
	s_add_u32 s26, s26, 0x10000
	s_addc_u32 s27, s27, 0
	s_waitcnt vmcnt(25)
	v_cvt_pk_bf16_f32 v43, v8, v9
	global_store_dword v42, v43, s[26:27]
	v_pk_fma_f32 v[8:9], v[8:9], v[158:159], v[126:127]
	s_add_u32 s26, s26, 0x10000
	s_addc_u32 s27, s27, 0
	s_waitcnt vmcnt(23)
	v_cvt_pk_bf16_f32 v44, v8, v9
	global_store_dword v42, v44, s[26:27]
	v_pk_fma_f32 v[8:9], v[8:9], v[160:161], v[128:129]
	s_add_u32 s26, s26, 0x10000
	s_addc_u32 s27, s27, 0
	s_waitcnt vmcnt(21)
	v_cvt_pk_bf16_f32 v43, v8, v9
	global_store_dword v42, v43, s[26:27]
	v_pk_fma_f32 v[8:9], v[8:9], v[162:163], v[130:131]
	s_add_u32 s26, s26, 0x10000
	s_addc_u32 s27, s27, 0
	s_waitcnt vmcnt(19)
	v_cvt_pk_bf16_f32 v44, v8, v9
	global_store_dword v42, v44, s[26:27]
	v_pk_fma_f32 v[8:9], v[8:9], v[164:165], v[132:133]
	s_add_u32 s26, s26, 0x10000
	s_addc_u32 s27, s27, 0
	s_waitcnt vmcnt(17)
	v_cvt_pk_bf16_f32 v43, v8, v9
	global_store_dword v42, v43, s[26:27]
	v_pk_fma_f32 v[8:9], v[8:9], v[166:167], v[134:135]
	s_add_u32 s26, s26, 0x10000
	s_addc_u32 s27, s27, 0
	s_waitcnt vmcnt(15)
	v_cvt_pk_bf16_f32 v44, v8, v9
	global_store_dword v42, v44, s[26:27]
	v_pk_fma_f32 v[8:9], v[8:9], v[168:169], v[136:137]
	s_add_u32 s26, s26, 0x10000
	s_addc_u32 s27, s27, 0
	v_add_u32_e32 v197, s15, v197
	v_cmp_lt_i32_e32 vcc, s20, v197
	s_or_b64 s[6:7], vcc, s[6:7]
	v_add_u32_e32 v1, s16, v1
	s_andn2_b64 exec, exec, s[6:7]
	s_cbranch_execnz .LBB0_1300
